# phase-4 epilogue: v_permlane16_swap + one dwordx4 store per row group (64-byte row segments) instead of two dwordx2
# baseline (speedup 1.0000x reference)
.LBB0_1095:
	v_lshl_or_b32 v122, s68, 8, v184
	v_ashrrev_i32_e32 v123, 31, v122
	v_lshl_add_u32 v201, s67, 8, v182
	v_lshlrev_b64 v[124:125], 2, v[122:123]
	v_lshlrev_b32_e32 v128, 1, v201
	v_or_b32_e32 v122, 16, v122
	v_ashrrev_i32_e32 v129, 31, v128
	v_ashrrev_i32_e32 v123, 31, v122
	v_lshl_add_u64 v[126:127], s[14:15], 0, v[124:125]
	v_lshl_add_u64 v[128:129], v[128:129], 2, s[82:83]
	v_lshlrev_b64 v[122:123], 2, v[122:123]
	global_load_dwordx2 v[202:203], v[128:129], off
	global_load_dwordx2 v[216:217], v[128:129], off offset:256
	global_load_dwordx2 v[218:219], v[128:129], off offset:384
	global_load_dwordx2 v[220:221], v[128:129], off offset:1024
	global_load_dwordx2 v[222:223], v[128:129], off offset:1152
	global_load_dwordx2 v[224:225], v[128:129], off offset:1280
	global_load_dwordx2 v[226:227], v[128:129], off offset:1408
	global_load_dwordx4 v[154:157], v[126:127], off
	global_load_dwordx4 v[146:149], v[126:127], off offset:512
	v_lshl_add_u64 v[126:127], s[14:15], 0, v[122:123]
	global_load_dwordx4 v[138:141], v[126:127], off
	s_nop 0
	global_load_dwordx4 v[126:129], v[126:127], off offset:512
	v_lshl_add_u64 v[124:125], s[18:19], 0, v[124:125]
	v_lshl_add_u64 v[122:123], s[18:19], 0, v[122:123]
	global_load_dwordx4 v[158:161], v[124:125], off
	global_load_dwordx4 v[150:153], v[124:125], off offset:512
	global_load_dwordx4 v[142:145], v[122:123], off
	s_nop 0
	global_load_dwordx4 v[122:125], v[122:123], off offset:512
	v_readlane_b32 s0, v251, 40
	v_lshl_or_b32 v178, s68, 7, v184
	v_readlane_b32 s1, v251, 41
	v_or_b32_e32 v210, 16, v201
	v_ashrrev_i32_e32 v179, 31, v178
	v_mov_b64_e32 v[176:177], s[0:1]
	v_lshlrev_b32_e32 v206, 1, v210
	v_mad_i64_i32 v[204:205], s[0:1], v201, s64, v[176:177]
	v_lshlrev_b64 v[178:179], 1, v[178:179]
	v_bfe_u32 v230, v162, 4, 1
	v_mul_u32_u24_e32 v230, 24, v230
	v_add_u32_e32 v178, v178, v230
	v_ashrrev_i32_e32 v207, 31, v206
	v_lshl_add_u64 v[204:205], v[204:205], 0, v[178:179]
	v_lshl_add_u64 v[206:207], v[206:207], 2, s[82:83]
	global_load_dwordx2 v[206:207], v[206:207], off
	s_mov_b32 s68, s65
	s_mov_b32 s67, s66
	s_mov_b64 s[26:27], s[54:55]
	s_mov_b64 s[28:29], s[8:9]
	s_waitcnt vmcnt(0)
	v_pk_mul_f32 v[202:203], v[202:203], s[46:47] op_sel_hi:[1,0]
	s_nop 0
	v_fma_f32 v211, -v202, v202, v203
	v_xor_b32_e32 v157, 0x80000000, v157
	v_pk_fma_f32 v[208:209], v[138:139], v[202:203], v[118:119] op_sel_hi:[1,0,1] neg_lo:[1,0,0] neg_hi:[1,0,0]
	v_xor_b32_e32 v119, 0x80000000, v141
	v_xor_b32_e32 v118, 0x80000000, v140
	v_pk_fma_f32 v[140:141], v[126:127], v[202:203], v[114:115] op_sel_hi:[1,0,1] neg_lo:[1,0,0] neg_hi:[1,0,0]
	v_add_f32_e32 v114, 0x3727c5ac, v211
	v_xor_b32_e32 v115, 0x80000000, v129
	v_mul_f32_e32 v129, 0x4b800000, v114
	v_cmp_gt_f32_e32 vcc, s63, v114
	v_xor_b32_e32 v156, 0x80000000, v156
	v_xor_b32_e32 v149, 0x80000000, v149
	v_cndmask_b32_e32 v114, v114, v129, vcc
	v_rsq_f32_e32 v129, v114
	v_xor_b32_e32 v114, 0x80000000, v128
	v_xor_b32_e32 v148, 0x80000000, v148
	v_pk_fma_f32 v[134:135], v[154:155], v[202:203], v[134:135] op_sel_hi:[1,0,1] neg_lo:[1,0,0] neg_hi:[1,0,0]
	v_mul_f32_e32 v128, 0x45800000, v129
	v_cndmask_b32_e32 v128, v129, v128, vcc
	v_pk_fma_f32 v[136:137], v[156:157], v[202:203], v[136:137] op_sel_hi:[1,0,1]
	v_pk_fma_f32 v[130:131], v[146:147], v[202:203], v[130:131] op_sel_hi:[1,0,1] neg_lo:[1,0,0] neg_hi:[1,0,0]
	v_pk_fma_f32 v[132:133], v[148:149], v[202:203], v[132:133] op_sel_hi:[1,0,1]
	v_pk_fma_f32 v[120:121], v[118:119], v[202:203], v[120:121] op_sel_hi:[1,0,1]
	v_pk_fma_f32 v[116:117], v[114:115], v[202:203], v[116:117] op_sel_hi:[1,0,1]
	v_pk_fma_f32 v[134:135], v[134:135], v[128:129], v[158:159] op_sel_hi:[1,0,1]
	v_pk_fma_f32 v[136:137], v[136:137], v[128:129], v[160:161] op_sel_hi:[1,0,1]
	v_pk_fma_f32 v[132:133], v[132:133], v[128:129], v[152:153] op_sel_hi:[1,0,1]
	v_pk_fma_f32 v[130:131], v[130:131], v[128:129], v[150:151] op_sel_hi:[1,0,1]
	v_pk_fma_f32 v[120:121], v[120:121], v[128:129], v[144:145] op_sel_hi:[1,0,1]
	v_pk_fma_f32 v[202:203], v[208:209], v[128:129], v[142:143] op_sel_hi:[1,0,1]
	v_pk_fma_f32 v[116:117], v[116:117], v[128:129], v[124:125] op_sel_hi:[1,0,1]
	v_pk_fma_f32 v[128:129], v[140:141], v[128:129], v[122:123] op_sel_hi:[1,0,1]
	v_mul_f32_e32 v140, 0xbfb8aa3b, v134
	v_mul_f32_e32 v141, 0xbfb8aa3b, v135
	v_exp_f32_e32 v140, v140
	v_mul_f32_e32 v208, 0xbfb8aa3b, v136
	v_mul_f32_e32 v209, 0xbfb8aa3b, v137
	v_exp_f32_e32 v141, v141
	v_exp_f32_e32 v208, v208
	v_exp_f32_e32 v209, v209
	v_add_f32_e32 v140, 1.0, v140
	v_add_f32_e32 v141, 1.0, v141
	v_rcp_f32_e32 v140, v140
	v_add_f32_e32 v208, 1.0, v208
	v_add_f32_e32 v209, 1.0, v209
	v_rcp_f32_e32 v141, v141
	v_mul_f32_e32 v213, 0xbfb8aa3b, v120
	v_rcp_f32_e32 v208, v208
	v_rcp_f32_e32 v209, v209
	v_mul_f32_e32 v211, 0xbfb8aa3b, v202
	v_mul_f32_e32 v212, 0xbfb8aa3b, v203
	v_mul_f32_e32 v214, 0xbfb8aa3b, v121
	v_exp_f32_e32 v213, v213
	v_exp_f32_e32 v211, v211
	v_exp_f32_e32 v212, v212
	v_exp_f32_e32 v214, v214
	v_mul_f32_e32 v134, v134, v140
	v_mul_f32_e32 v135, v135, v141
	v_mul_f32_e32 v130, v130, v134
	v_mul_f32_e32 v136, v136, v208
	v_mul_f32_e32 v137, v137, v209
	v_mul_f32_e32 v131, v131, v135
	v_cvt_pk_bf16_f32 v130, v130, v131
	v_mul_f32_e32 v132, v132, v136
	v_mul_f32_e32 v133, v133, v137
	v_cvt_pk_bf16_f32 v131, v132, v133
	v_mov_b32_e32 v232, v130
	v_mov_b32_e32 v233, v131
	v_add_f32_e32 v130, 1.0, v213
	v_add_f32_e32 v211, 1.0, v211
	v_add_f32_e32 v212, 1.0, v212
	v_rcp_f32_e32 v130, v130
	v_add_f32_e32 v131, 1.0, v214
	v_rcp_f32_e32 v211, v211
	v_rcp_f32_e32 v212, v212
	v_rcp_f32_e32 v131, v131
	v_mul_f32_e32 v120, v120, v130
	v_mul_f32_e32 v140, v202, v211
	v_mul_f32_e32 v141, v203, v212
	v_mul_f32_e32 v120, v116, v120
	v_mul_f32_e32 v116, v121, v131
	v_mul_f32_e32 v128, v128, v140
	v_mul_f32_e32 v129, v129, v141
	v_mul_f32_e32 v117, v117, v116
	v_cvt_pk_bf16_f32 v116, v128, v129
	v_or_b32_e32 v134, 32, v201
	v_cvt_pk_bf16_f32 v117, v120, v117
	v_mov_b32_e32 v234, v116
	v_mov_b32_e32 v235, v117
	s_nop 1
	v_permlane16_swap_b32_e32 v232, v234
	v_permlane16_swap_b32_e32 v233, v235
	global_store_dwordx4 v[204:205], v[232:235], off
	v_lshlrev_b32_e32 v116, 1, v134
	v_ashrrev_i32_e32 v117, 31, v116
	v_lshl_add_u64 v[116:117], v[116:117], 2, s[82:83]
	v_mov_b32_e32 v116, v216
	v_mov_b32_e32 v117, v217
	v_pk_mul_f32 v[128:129], v[206:207], s[46:47] op_sel_hi:[1,0]
	v_mad_i64_i32 v[120:121], s[0:1], v210, s64, v[176:177]
	v_mov_b32_e32 v131, v128
	v_mov_b32_e32 v133, v129
	v_pk_fma_f32 v[110:111], v[154:155], v[128:129], v[110:111] op_sel_hi:[1,0,1] neg_lo:[1,0,0] neg_hi:[1,0,0]
	v_pk_fma_f32 v[112:113], v[156:157], v[128:129], v[112:113] op_sel_hi:[1,0,1]
	v_pk_fma_f32 v[106:107], v[146:147], v[128:129], v[106:107] op_sel_hi:[1,0,1] neg_lo:[1,0,0] neg_hi:[1,0,0]
	v_pk_fma_f32 v[108:109], v[148:149], v[128:129], v[108:109] op_sel_hi:[1,0,1]
	v_pk_fma_f32 v[102:103], v[138:139], v[128:129], v[102:103] op_sel_hi:[1,0,1] neg_lo:[1,0,0] neg_hi:[1,0,0]
	v_pk_fma_f32 v[104:105], v[118:119], v[128:129], v[104:105] op_sel_hi:[1,0,1]
	v_pk_fma_f32 v[98:99], v[126:127], v[128:129], v[98:99] op_sel_hi:[1,0,1] neg_lo:[1,0,0] neg_hi:[1,0,0]
	v_pk_fma_f32 v[100:101], v[114:115], v[128:129], v[100:101] op_sel_hi:[1,0,1]
	v_lshl_add_u64 v[120:121], v[120:121], 0, v[178:179]
	v_pk_mul_f32 v[116:117], v[116:117], s[46:47] op_sel_hi:[1,0]
	s_nop 0
	v_mov_b32_e32 v130, v116
	v_mov_b32_e32 v132, v117
	v_pk_fma_f32 v[130:131], v[130:131], v[130:131], v[132:133] neg_lo:[1,0,0] neg_hi:[1,0,0]
	v_pk_fma_f32 v[94:95], v[154:155], v[116:117], v[94:95] op_sel_hi:[1,0,1] neg_lo:[1,0,0] neg_hi:[1,0,0]
	v_pk_add_f32 v[130:131], v[130:131], s[52:53] op_sel_hi:[1,0]
	v_pk_fma_f32 v[96:97], v[156:157], v[116:117], v[96:97] op_sel_hi:[1,0,1]
	v_mul_f32_e32 v132, 0x4b800000, v131
	v_cmp_gt_f32_e32 vcc, s63, v131
	v_mul_f32_e32 v133, 0x4b800000, v130
	v_cmp_gt_f32_e64 s[0:1], s63, v130
	v_cndmask_b32_e32 v131, v131, v132, vcc
	v_rsq_f32_e32 v131, v131
	v_cndmask_b32_e64 v130, v130, v133, s[0:1]
	v_rsq_f32_e32 v130, v130
	v_pk_fma_f32 v[90:91], v[146:147], v[116:117], v[90:91] op_sel_hi:[1,0,1] neg_lo:[1,0,0] neg_hi:[1,0,0]
	v_mul_f32_e32 v128, 0x45800000, v131
	v_cndmask_b32_e32 v128, v131, v128, vcc
	v_mul_f32_e32 v129, 0x45800000, v130
	v_pk_fma_f32 v[112:113], v[112:113], v[128:129], v[160:161] op_sel_hi:[1,0,1]
	v_pk_fma_f32 v[104:105], v[104:105], v[128:129], v[144:145] op_sel_hi:[1,0,1]
	v_pk_fma_f32 v[102:103], v[102:103], v[128:129], v[142:143] op_sel_hi:[1,0,1]
	v_pk_fma_f32 v[110:111], v[110:111], v[128:129], v[158:159] op_sel_hi:[1,0,1]
	v_mul_f32_e32 v131, 0xbfb8aa3b, v112
	v_mul_f32_e32 v132, 0xbfb8aa3b, v113
	v_mul_f32_e32 v135, 0xbfb8aa3b, v103
	v_mul_f32_e32 v137, 0xbfb8aa3b, v105
	v_cndmask_b32_e64 v130, v130, v129, s[0:1]
	v_pk_fma_f32 v[108:109], v[108:109], v[128:129], v[152:153] op_sel_hi:[1,0,1]
	v_pk_fma_f32 v[106:107], v[106:107], v[128:129], v[150:151] op_sel_hi:[1,0,1]
	v_pk_fma_f32 v[100:101], v[100:101], v[128:129], v[124:125] op_sel_hi:[1,0,1]
	v_pk_fma_f32 v[98:99], v[98:99], v[128:129], v[122:123] op_sel_hi:[1,0,1]
	v_mul_f32_e32 v128, 0xbfb8aa3b, v110
	v_mul_f32_e32 v129, 0xbfb8aa3b, v111
	v_mul_f32_e32 v133, 0xbfb8aa3b, v102
	v_mul_f32_e32 v136, 0xbfb8aa3b, v104
	v_exp_f32_e32 v131, v131
	v_exp_f32_e32 v132, v132
	v_exp_f32_e32 v135, v135
	v_exp_f32_e32 v137, v137
	v_exp_f32_e32 v128, v128
	v_exp_f32_e32 v129, v129
	v_exp_f32_e32 v133, v133
	v_exp_f32_e32 v136, v136
	v_add_f32_e32 v131, 1.0, v131
	v_add_f32_e32 v132, 1.0, v132
	v_add_f32_e32 v135, 1.0, v135
	v_add_f32_e32 v137, 1.0, v137
	v_add_f32_e32 v128, 1.0, v128
	v_add_f32_e32 v129, 1.0, v129
	v_add_f32_e32 v133, 1.0, v133
	v_add_f32_e32 v136, 1.0, v136
	v_rcp_f32_e32 v131, v131
	v_rcp_f32_e32 v132, v132
	v_rcp_f32_e32 v135, v135
	v_rcp_f32_e32 v137, v137
	v_rcp_f32_e32 v128, v128
	v_rcp_f32_e32 v129, v129
	v_rcp_f32_e32 v133, v133
	v_rcp_f32_e32 v136, v136
	v_mul_f32_e32 v112, v112, v131
	v_mul_f32_e32 v113, v113, v132
	v_mul_f32_e32 v103, v103, v135
	v_mul_f32_e32 v105, v105, v137
	v_mul_f32_e32 v110, v110, v128
	v_mul_f32_e32 v111, v111, v129
	v_mul_f32_e32 v102, v102, v133
	v_mul_f32_e32 v104, v104, v136
	v_mul_f32_e32 v108, v108, v112
	v_mul_f32_e32 v109, v109, v113
	v_mul_f32_e32 v103, v99, v103
	v_mul_f32_e32 v101, v101, v105
	v_cvt_pk_bf16_f32 v99, v108, v109
	v_pk_fma_f32 v[94:95], v[94:95], v[130:131], v[158:159] op_sel_hi:[1,0,1]
	v_mul_f32_e32 v106, v106, v110
	v_mul_f32_e32 v107, v107, v111
	v_mul_f32_e32 v102, v98, v102
	v_mul_f32_e32 v100, v100, v104
	v_cvt_pk_bf16_f32 v98, v106, v107
	v_mov_b32_e32 v232, v98
	v_mov_b32_e32 v233, v99
	v_cvt_pk_bf16_f32 v99, v100, v101
	v_mul_f32_e32 v101, 0xbfb8aa3b, v94
	v_exp_f32_e32 v101, v101
	v_cvt_pk_bf16_f32 v98, v102, v103
	v_mul_f32_e32 v102, 0xbfb8aa3b, v95
	v_exp_f32_e32 v102, v102
	v_add_f32_e32 v101, 1.0, v101
	v_rcp_f32_e32 v101, v101
	v_pk_fma_f32 v[96:97], v[96:97], v[130:131], v[160:161] op_sel_hi:[1,0,1]
	v_pk_fma_f32 v[90:91], v[90:91], v[130:131], v[150:151] op_sel_hi:[1,0,1]
	v_pk_fma_f32 v[92:93], v[148:149], v[116:117], v[92:93] op_sel_hi:[1,0,1]
	v_mul_f32_e32 v94, v94, v101
	v_mul_f32_e32 v90, v90, v94
	v_add_f32_e32 v94, 1.0, v102
	v_mul_f32_e32 v101, 0xbfb8aa3b, v96
	v_rcp_f32_e32 v94, v94
	v_exp_f32_e32 v101, v101
	v_mul_f32_e32 v102, 0xbfb8aa3b, v97
	v_exp_f32_e32 v102, v102
	v_mul_f32_e32 v94, v95, v94
	v_add_f32_e32 v95, 1.0, v101
	v_rcp_f32_e32 v95, v95
	v_add_f32_e32 v101, 1.0, v102
	v_rcp_f32_e32 v101, v101
	v_pk_fma_f32 v[92:93], v[92:93], v[130:131], v[152:153] op_sel_hi:[1,0,1]
	v_mul_f32_e32 v91, v91, v94
	v_mul_f32_e32 v94, v96, v95
	v_or_b32_e32 v100, 48, v201
	v_mul_f32_e32 v92, v92, v94
	v_mul_f32_e32 v94, v97, v101
	v_mov_b32_e32 v234, v98
	v_mov_b32_e32 v235, v99
	s_nop 1
	v_permlane16_swap_b32_e32 v232, v234
	v_permlane16_swap_b32_e32 v233, v235
	global_store_dwordx4 v[120:121], v[232:235], off
	v_lshlrev_b32_e32 v98, 1, v100
	v_mul_f32_e32 v93, v93, v94
	v_ashrrev_i32_e32 v99, 31, v98
	v_cvt_pk_bf16_f32 v90, v90, v91
	v_cvt_pk_bf16_f32 v91, v92, v93
	v_mad_i64_i32 v[92:93], s[0:1], v134, s64, v[176:177]
	v_pk_fma_f32 v[86:87], v[138:139], v[116:117], v[86:87] op_sel_hi:[1,0,1] neg_lo:[1,0,0] neg_hi:[1,0,0]
	v_lshl_add_u64 v[98:99], v[98:99], 2, s[82:83]
	v_lshl_add_u64 v[92:93], v[92:93], 0, v[178:179]
	v_pk_fma_f32 v[86:87], v[86:87], v[130:131], v[142:143] op_sel_hi:[1,0,1]
	v_mov_b32_e32 v98, v218
	v_mov_b32_e32 v99, v219
	v_pk_fma_f32 v[88:89], v[118:119], v[116:117], v[88:89] op_sel_hi:[1,0,1]
	v_mov_b32_e32 v232, v90
	v_mov_b32_e32 v233, v91
	v_mul_f32_e32 v90, 0xbfb8aa3b, v86
	v_exp_f32_e32 v90, v90
	v_mul_f32_e32 v91, 0xbfb8aa3b, v87
	v_exp_f32_e32 v91, v91
	v_pk_fma_f32 v[82:83], v[126:127], v[116:117], v[82:83] op_sel_hi:[1,0,1] neg_lo:[1,0,0] neg_hi:[1,0,0]
	v_add_f32_e32 v90, 1.0, v90
	v_rcp_f32_e32 v90, v90
	v_pk_fma_f32 v[88:89], v[88:89], v[130:131], v[144:145] op_sel_hi:[1,0,1]
	v_pk_fma_f32 v[82:83], v[82:83], v[130:131], v[122:123] op_sel_hi:[1,0,1]
	v_pk_fma_f32 v[84:85], v[114:115], v[116:117], v[84:85] op_sel_hi:[1,0,1]
	v_mul_f32_e32 v86, v86, v90
	v_mul_f32_e32 v82, v82, v86
	v_add_f32_e32 v86, 1.0, v91
	v_mul_f32_e32 v90, 0xbfb8aa3b, v88
	v_rcp_f32_e32 v86, v86
	v_exp_f32_e32 v90, v90
	v_mul_f32_e32 v91, 0xbfb8aa3b, v89
	v_exp_f32_e32 v91, v91
	v_mul_f32_e32 v86, v87, v86
	v_add_f32_e32 v87, 1.0, v90
	v_rcp_f32_e32 v87, v87
	v_add_f32_e32 v90, 1.0, v91
	v_rcp_f32_e32 v90, v90
	v_pk_fma_f32 v[84:85], v[84:85], v[130:131], v[124:125] op_sel_hi:[1,0,1]
	v_mul_f32_e32 v83, v83, v86
	v_mul_f32_e32 v86, v88, v87
	v_mul_f32_e32 v84, v84, v86
	v_mul_f32_e32 v86, v89, v90
	v_cvt_pk_bf16_f32 v82, v82, v83
	v_add_u32_e32 v90, 0x80, v201
	v_mul_f32_e32 v85, v85, v86
	v_cvt_pk_bf16_f32 v83, v84, v85
	v_mov_b32_e32 v234, v82
	v_mov_b32_e32 v235, v83
	s_nop 1
	v_permlane16_swap_b32_e32 v232, v234
	v_permlane16_swap_b32_e32 v233, v235
	global_store_dwordx4 v[92:93], v[232:235], off
	v_lshlrev_b32_e32 v82, 1, v90
	v_ashrrev_i32_e32 v83, 31, v82
	v_lshl_add_u64 v[82:83], v[82:83], 2, s[82:83]
	v_mov_b32_e32 v82, v220
	v_mov_b32_e32 v83, v221
	v_pk_mul_f32 v[84:85], v[98:99], s[46:47] op_sel_hi:[1,0]
	s_nop 0
	v_mov_b32_e32 v87, v84
	v_mov_b32_e32 v89, v85
	v_pk_fma_f32 v[78:79], v[154:155], v[84:85], v[78:79] op_sel_hi:[1,0,1] neg_lo:[1,0,0] neg_hi:[1,0,0]
	v_pk_fma_f32 v[80:81], v[156:157], v[84:85], v[80:81] op_sel_hi:[1,0,1]
	v_pk_fma_f32 v[76:77], v[148:149], v[84:85], v[76:77] op_sel_hi:[1,0,1]
	v_pk_fma_f32 v[74:75], v[146:147], v[84:85], v[74:75] op_sel_hi:[1,0,1] neg_lo:[1,0,0] neg_hi:[1,0,0]
	v_pk_fma_f32 v[70:71], v[138:139], v[84:85], v[70:71] op_sel_hi:[1,0,1] neg_lo:[1,0,0] neg_hi:[1,0,0]
	v_pk_fma_f32 v[72:73], v[118:119], v[84:85], v[72:73] op_sel_hi:[1,0,1]
	v_pk_fma_f32 v[66:67], v[126:127], v[84:85], v[66:67] op_sel_hi:[1,0,1] neg_lo:[1,0,0] neg_hi:[1,0,0]
	v_pk_fma_f32 v[68:69], v[114:115], v[84:85], v[68:69] op_sel_hi:[1,0,1]
	v_pk_mul_f32 v[82:83], v[82:83], s[46:47] op_sel_hi:[1,0]
	s_nop 0
	v_mov_b32_e32 v86, v82
	v_mov_b32_e32 v88, v83
	v_pk_fma_f32 v[86:87], v[86:87], v[86:87], v[88:89] neg_lo:[1,0,0] neg_hi:[1,0,0]
	v_pk_fma_f32 v[62:63], v[154:155], v[82:83], v[62:63] op_sel_hi:[1,0,1] neg_lo:[1,0,0] neg_hi:[1,0,0]
	v_pk_add_f32 v[86:87], v[86:87], s[52:53] op_sel_hi:[1,0]
	v_pk_fma_f32 v[64:65], v[156:157], v[82:83], v[64:65] op_sel_hi:[1,0,1]
	v_mul_f32_e32 v88, 0x4b800000, v87
	v_cmp_gt_f32_e32 vcc, s63, v87
	v_cmp_gt_f32_e64 s[0:1], s63, v86
	v_pk_fma_f32 v[58:59], v[146:147], v[82:83], v[58:59] op_sel_hi:[1,0,1] neg_lo:[1,0,0] neg_hi:[1,0,0]
	v_cndmask_b32_e32 v87, v87, v88, vcc
	v_mul_f32_e32 v88, 0x4b800000, v86
	v_rsq_f32_e32 v87, v87
	v_cndmask_b32_e64 v86, v86, v88, s[0:1]
	v_rsq_f32_e32 v88, v86
	v_pk_fma_f32 v[60:61], v[148:149], v[82:83], v[60:61] op_sel_hi:[1,0,1]
	v_mul_f32_e32 v86, 0x45800000, v87
	v_cndmask_b32_e32 v86, v87, v86, vcc
	v_mul_f32_e32 v87, 0x45800000, v88
	v_pk_fma_f32 v[78:79], v[78:79], v[86:87], v[158:159] op_sel_hi:[1,0,1]
	v_cndmask_b32_e64 v88, v88, v87, s[0:1]
	v_pk_fma_f32 v[80:81], v[80:81], v[86:87], v[160:161] op_sel_hi:[1,0,1]
	v_mul_f32_e32 v87, 0xbfb8aa3b, v78
	v_exp_f32_e32 v87, v87
	v_mul_f32_e32 v89, 0xbfb8aa3b, v79
	v_exp_f32_e32 v89, v89
	v_pk_fma_f32 v[54:55], v[138:139], v[82:83], v[54:55] op_sel_hi:[1,0,1] neg_lo:[1,0,0] neg_hi:[1,0,0]
	v_pk_fma_f32 v[76:77], v[76:77], v[86:87], v[152:153] op_sel_hi:[1,0,1]
	v_add_f32_e32 v87, 1.0, v87
	v_rcp_f32_e32 v87, v87
	v_pk_fma_f32 v[56:57], v[118:119], v[82:83], v[56:57] op_sel_hi:[1,0,1]
	v_pk_fma_f32 v[50:51], v[126:127], v[82:83], v[50:51] op_sel_hi:[1,0,1] neg_lo:[1,0,0] neg_hi:[1,0,0]
	v_pk_fma_f32 v[52:53], v[114:115], v[82:83], v[52:53] op_sel_hi:[1,0,1]
	v_pk_fma_f32 v[74:75], v[74:75], v[86:87], v[150:151] op_sel_hi:[1,0,1]
	v_mul_f32_e32 v78, v78, v87
	v_mul_f32_e32 v74, v74, v78
	v_add_f32_e32 v78, 1.0, v89
	v_mul_f32_e32 v87, 0xbfb8aa3b, v80
	v_rcp_f32_e32 v78, v78
	v_exp_f32_e32 v87, v87
	v_mul_f32_e32 v89, 0xbfb8aa3b, v81
	v_exp_f32_e32 v89, v89
	v_mul_f32_e32 v78, v79, v78
	v_add_f32_e32 v79, 1.0, v87
	v_rcp_f32_e32 v79, v79
	v_add_f32_e32 v87, 1.0, v89
	v_rcp_f32_e32 v87, v87
	v_mul_f32_e32 v75, v75, v78
	v_mul_f32_e32 v78, v80, v79
	v_mul_f32_e32 v76, v76, v78
	v_mul_f32_e32 v78, v81, v87
	v_mul_f32_e32 v77, v77, v78
	v_cvt_pk_bf16_f32 v74, v74, v75
	v_cvt_pk_bf16_f32 v75, v76, v77
	v_mad_i64_i32 v[76:77], s[0:1], v100, s64, v[176:177]
	v_lshl_add_u64 v[76:77], v[76:77], 0, v[178:179]
	v_pk_fma_f32 v[70:71], v[70:71], v[86:87], v[142:143] op_sel_hi:[1,0,1]
	v_mov_b32_e32 v232, v74
	v_mov_b32_e32 v233, v75
	v_mul_f32_e32 v74, 0xbfb8aa3b, v70
	v_exp_f32_e32 v74, v74
	v_mul_f32_e32 v75, 0xbfb8aa3b, v71
	v_exp_f32_e32 v75, v75
	v_pk_fma_f32 v[72:73], v[72:73], v[86:87], v[144:145] op_sel_hi:[1,0,1]
	v_add_f32_e32 v74, 1.0, v74
	v_rcp_f32_e32 v74, v74
	v_pk_fma_f32 v[66:67], v[66:67], v[86:87], v[122:123] op_sel_hi:[1,0,1]
	v_pk_fma_f32 v[68:69], v[68:69], v[86:87], v[124:125] op_sel_hi:[1,0,1]
	v_pk_fma_f32 v[62:63], v[62:63], v[88:89], v[158:159] op_sel_hi:[1,0,1]
	v_mul_f32_e32 v70, v70, v74
	v_mul_f32_e32 v66, v66, v70
	v_add_f32_e32 v70, 1.0, v75
	v_mul_f32_e32 v74, 0xbfb8aa3b, v72
	v_rcp_f32_e32 v70, v70
	v_exp_f32_e32 v74, v74
	v_mul_f32_e32 v75, 0xbfb8aa3b, v73
	v_exp_f32_e32 v75, v75
	v_mul_f32_e32 v70, v71, v70
	v_add_f32_e32 v71, 1.0, v74
	v_rcp_f32_e32 v71, v71
	v_add_f32_e32 v74, 1.0, v75
	v_rcp_f32_e32 v74, v74
	v_mul_f32_e32 v67, v67, v70
	v_mul_f32_e32 v70, v72, v71
	v_mul_f32_e32 v68, v68, v70
	v_mul_f32_e32 v70, v73, v74
	v_mul_f32_e32 v69, v69, v70
	v_cvt_pk_bf16_f32 v66, v66, v67
	v_cvt_pk_bf16_f32 v67, v68, v69
	v_mul_f32_e32 v69, 0xbfb8aa3b, v62
	v_exp_f32_e32 v69, v69
	v_mul_f32_e32 v70, 0xbfb8aa3b, v63
	v_exp_f32_e32 v70, v70
	v_pk_fma_f32 v[64:65], v[64:65], v[88:89], v[160:161] op_sel_hi:[1,0,1]
	v_add_f32_e32 v69, 1.0, v69
	v_rcp_f32_e32 v69, v69
	v_pk_fma_f32 v[58:59], v[58:59], v[88:89], v[150:151] op_sel_hi:[1,0,1]
	v_pk_fma_f32 v[60:61], v[60:61], v[88:89], v[152:153] op_sel_hi:[1,0,1]
	v_add_u32_e32 v68, 0x90, v201
	v_mul_f32_e32 v62, v62, v69
	v_mul_f32_e32 v58, v58, v62
	v_add_f32_e32 v62, 1.0, v70
	v_mul_f32_e32 v69, 0xbfb8aa3b, v64
	v_rcp_f32_e32 v62, v62
	v_exp_f32_e32 v69, v69
	v_mul_f32_e32 v70, 0xbfb8aa3b, v65
	v_exp_f32_e32 v70, v70
	v_mul_f32_e32 v62, v63, v62
	v_add_f32_e32 v63, 1.0, v69
	v_rcp_f32_e32 v63, v63
	v_add_f32_e32 v69, 1.0, v70
	v_rcp_f32_e32 v69, v69
	v_mul_f32_e32 v59, v59, v62
	v_mul_f32_e32 v62, v64, v63
	v_mul_f32_e32 v60, v60, v62
	v_mul_f32_e32 v62, v65, v69
	v_mov_b32_e32 v234, v66
	v_mov_b32_e32 v235, v67
	s_nop 1
	v_permlane16_swap_b32_e32 v232, v234
	v_permlane16_swap_b32_e32 v233, v235
	global_store_dwordx4 v[76:77], v[232:235], off
	v_lshlrev_b32_e32 v66, 1, v68
	v_mul_f32_e32 v61, v61, v62
	v_ashrrev_i32_e32 v67, 31, v66
	v_cvt_pk_bf16_f32 v58, v58, v59
	v_cvt_pk_bf16_f32 v59, v60, v61
	v_mad_i64_i32 v[60:61], s[0:1], v90, s64, v[176:177]
	v_lshl_add_u64 v[66:67], v[66:67], 2, s[82:83]
	v_lshl_add_u64 v[60:61], v[60:61], 0, v[178:179]
	v_pk_fma_f32 v[54:55], v[54:55], v[88:89], v[142:143] op_sel_hi:[1,0,1]
	v_mov_b32_e32 v66, v222
	v_mov_b32_e32 v67, v223
	v_pk_fma_f32 v[56:57], v[56:57], v[88:89], v[144:145] op_sel_hi:[1,0,1]
	v_mov_b32_e32 v232, v58
	v_mov_b32_e32 v233, v59
	v_mul_f32_e32 v58, 0xbfb8aa3b, v54
	v_exp_f32_e32 v58, v58
	v_mul_f32_e32 v59, 0xbfb8aa3b, v55
	v_exp_f32_e32 v59, v59
	v_pk_fma_f32 v[50:51], v[50:51], v[88:89], v[122:123] op_sel_hi:[1,0,1]
	v_add_f32_e32 v58, 1.0, v58
	v_rcp_f32_e32 v58, v58
	v_pk_fma_f32 v[52:53], v[52:53], v[88:89], v[124:125] op_sel_hi:[1,0,1]
	v_mul_f32_e32 v54, v54, v58
	v_mul_f32_e32 v50, v50, v54
	v_add_f32_e32 v54, 1.0, v59
	v_mul_f32_e32 v58, 0xbfb8aa3b, v56
	v_rcp_f32_e32 v54, v54
	v_exp_f32_e32 v58, v58
	v_mul_f32_e32 v59, 0xbfb8aa3b, v57
	v_exp_f32_e32 v59, v59
	v_mul_f32_e32 v54, v55, v54
	v_add_f32_e32 v55, 1.0, v58
	v_rcp_f32_e32 v55, v55
	v_add_f32_e32 v58, 1.0, v59
	v_rcp_f32_e32 v58, v58
	v_mul_f32_e32 v51, v51, v54
	v_mul_f32_e32 v54, v56, v55
	v_mul_f32_e32 v52, v52, v54
	v_mul_f32_e32 v54, v57, v58
	v_cvt_pk_bf16_f32 v50, v50, v51
	v_add_u32_e32 v58, 0xa0, v201
	v_mul_f32_e32 v53, v53, v54
	v_cvt_pk_bf16_f32 v51, v52, v53
	v_mov_b32_e32 v234, v50
	v_mov_b32_e32 v235, v51
	s_nop 1
	v_permlane16_swap_b32_e32 v232, v234
	v_permlane16_swap_b32_e32 v233, v235
	global_store_dwordx4 v[60:61], v[232:235], off
	v_lshlrev_b32_e32 v50, 1, v58
	v_ashrrev_i32_e32 v51, 31, v50
	v_lshl_add_u64 v[50:51], v[50:51], 2, s[82:83]
	v_mov_b32_e32 v50, v224
	v_mov_b32_e32 v51, v225
	v_pk_mul_f32 v[52:53], v[66:67], s[46:47] op_sel_hi:[1,0]
	s_nop 0
	v_mov_b32_e32 v55, v52
	v_mov_b32_e32 v57, v53
	v_pk_fma_f32 v[46:47], v[154:155], v[52:53], v[46:47] op_sel_hi:[1,0,1] neg_lo:[1,0,0] neg_hi:[1,0,0]
	v_pk_fma_f32 v[48:49], v[156:157], v[52:53], v[48:49] op_sel_hi:[1,0,1]
	v_pk_fma_f32 v[44:45], v[148:149], v[52:53], v[44:45] op_sel_hi:[1,0,1]
	v_pk_fma_f32 v[42:43], v[146:147], v[52:53], v[42:43] op_sel_hi:[1,0,1] neg_lo:[1,0,0] neg_hi:[1,0,0]
	v_pk_fma_f32 v[38:39], v[138:139], v[52:53], v[38:39] op_sel_hi:[1,0,1] neg_lo:[1,0,0] neg_hi:[1,0,0]
	v_pk_fma_f32 v[40:41], v[118:119], v[52:53], v[40:41] op_sel_hi:[1,0,1]
	v_pk_fma_f32 v[34:35], v[126:127], v[52:53], v[34:35] op_sel_hi:[1,0,1] neg_lo:[1,0,0] neg_hi:[1,0,0]
	v_pk_fma_f32 v[36:37], v[114:115], v[52:53], v[36:37] op_sel_hi:[1,0,1]
	v_pk_mul_f32 v[50:51], v[50:51], s[46:47] op_sel_hi:[1,0]
	s_nop 0
	v_mov_b32_e32 v54, v50
	v_mov_b32_e32 v56, v51
	v_pk_fma_f32 v[54:55], v[54:55], v[54:55], v[56:57] neg_lo:[1,0,0] neg_hi:[1,0,0]
	v_pk_fma_f32 v[30:31], v[154:155], v[50:51], v[30:31] op_sel_hi:[1,0,1] neg_lo:[1,0,0] neg_hi:[1,0,0]
	v_pk_add_f32 v[54:55], v[54:55], s[52:53] op_sel_hi:[1,0]
	v_pk_fma_f32 v[32:33], v[156:157], v[50:51], v[32:33] op_sel_hi:[1,0,1]
	v_mul_f32_e32 v56, 0x4b800000, v55
	v_cmp_gt_f32_e32 vcc, s63, v55
	v_pk_fma_f32 v[26:27], v[146:147], v[50:51], v[26:27] op_sel_hi:[1,0,1] neg_lo:[1,0,0] neg_hi:[1,0,0]
	v_pk_fma_f32 v[28:29], v[148:149], v[50:51], v[28:29] op_sel_hi:[1,0,1]
	v_cndmask_b32_e32 v55, v55, v56, vcc
	v_rsq_f32_e32 v55, v55
	v_pk_fma_f32 v[22:23], v[138:139], v[50:51], v[22:23] op_sel_hi:[1,0,1] neg_lo:[1,0,0] neg_hi:[1,0,0]
	v_pk_fma_f32 v[24:25], v[118:119], v[50:51], v[24:25] op_sel_hi:[1,0,1]
	v_pk_fma_f32 v[18:19], v[126:127], v[50:51], v[18:19] op_sel_hi:[1,0,1] neg_lo:[1,0,0] neg_hi:[1,0,0]
	v_mul_f32_e32 v56, 0x45800000, v55
	v_cndmask_b32_e32 v56, v55, v56, vcc
	v_pk_fma_f32 v[46:47], v[46:47], v[56:57], v[158:159] op_sel_hi:[1,0,1]
	v_pk_fma_f32 v[48:49], v[48:49], v[56:57], v[160:161] op_sel_hi:[1,0,1]
	v_mul_f32_e32 v55, 0xbfb8aa3b, v46
	v_exp_f32_e32 v55, v55
	v_pk_fma_f32 v[44:45], v[44:45], v[56:57], v[152:153] op_sel_hi:[1,0,1]
	v_mul_f32_e32 v57, 0xbfb8aa3b, v47
	v_exp_f32_e32 v57, v57
	v_add_f32_e32 v55, 1.0, v55
	v_rcp_f32_e32 v55, v55
	v_cmp_gt_f32_e32 vcc, s63, v54
	v_pk_fma_f32 v[42:43], v[42:43], v[56:57], v[150:151] op_sel_hi:[1,0,1]
	v_pk_fma_f32 v[20:21], v[114:115], v[50:51], v[20:21] op_sel_hi:[1,0,1]
	v_mul_f32_e32 v46, v46, v55
	v_mul_f32_e32 v42, v42, v46
	v_add_f32_e32 v46, 1.0, v57
	v_mul_f32_e32 v55, 0xbfb8aa3b, v48
	v_rcp_f32_e32 v46, v46
	v_exp_f32_e32 v55, v55
	v_mul_f32_e32 v57, 0xbfb8aa3b, v49
	v_exp_f32_e32 v57, v57
	v_mul_f32_e32 v46, v47, v46
	v_add_f32_e32 v47, 1.0, v55
	v_rcp_f32_e32 v47, v47
	v_add_f32_e32 v55, 1.0, v57
	v_rcp_f32_e32 v55, v55
	v_mul_f32_e32 v43, v43, v46
	v_mul_f32_e32 v46, v48, v47
	v_mul_f32_e32 v44, v44, v46
	v_mul_f32_e32 v46, v49, v55
	v_mul_f32_e32 v45, v45, v46
	v_cvt_pk_bf16_f32 v42, v42, v43
	v_cvt_pk_bf16_f32 v43, v44, v45
	v_mad_i64_i32 v[44:45], s[0:1], v68, s64, v[176:177]
	v_lshl_add_u64 v[44:45], v[44:45], 0, v[178:179]
	v_pk_fma_f32 v[38:39], v[38:39], v[56:57], v[142:143] op_sel_hi:[1,0,1]
	v_mov_b32_e32 v232, v42
	v_mov_b32_e32 v233, v43
	v_mul_f32_e32 v42, 0xbfb8aa3b, v38
	v_exp_f32_e32 v42, v42
	v_mul_f32_e32 v43, 0xbfb8aa3b, v39
	v_exp_f32_e32 v43, v43
	v_pk_fma_f32 v[40:41], v[40:41], v[56:57], v[144:145] op_sel_hi:[1,0,1]
	v_add_f32_e32 v42, 1.0, v42
	v_rcp_f32_e32 v42, v42
	v_pk_fma_f32 v[34:35], v[34:35], v[56:57], v[122:123] op_sel_hi:[1,0,1]
	v_pk_fma_f32 v[36:37], v[36:37], v[56:57], v[124:125] op_sel_hi:[1,0,1]
	v_mul_f32_e32 v38, v38, v42
	v_mul_f32_e32 v34, v34, v38
	v_add_f32_e32 v38, 1.0, v43
	v_mul_f32_e32 v42, 0xbfb8aa3b, v40
	v_rcp_f32_e32 v38, v38
	v_exp_f32_e32 v42, v42
	v_mul_f32_e32 v43, 0xbfb8aa3b, v41
	v_exp_f32_e32 v43, v43
	v_mul_f32_e32 v38, v39, v38
	v_add_f32_e32 v39, 1.0, v42
	v_rcp_f32_e32 v39, v39
	v_add_f32_e32 v42, 1.0, v43
	v_rcp_f32_e32 v42, v42
	v_mul_f32_e32 v35, v35, v38
	v_mul_f32_e32 v38, v40, v39
	v_mul_f32_e32 v36, v36, v38
	v_mul_f32_e32 v38, v41, v42
	v_mul_f32_e32 v37, v37, v38
	v_cvt_pk_bf16_f32 v34, v34, v35
	v_cvt_pk_bf16_f32 v35, v36, v37
	v_add_u32_e32 v37, 0xb0, v201
	v_mov_b32_e32 v234, v34
	v_mov_b32_e32 v235, v35
	s_nop 1
	v_permlane16_swap_b32_e32 v232, v234
	v_permlane16_swap_b32_e32 v233, v235
	global_store_dwordx4 v[44:45], v[232:235], off
	v_lshlrev_b32_e32 v34, 1, v37
	v_ashrrev_i32_e32 v35, 31, v34
	v_lshl_add_u64 v[34:35], v[34:35], 2, s[82:83]
	v_mov_b32_e32 v34, v226
	v_mov_b32_e32 v35, v227
	v_mul_f32_e32 v36, 0x4b800000, v54
	v_cndmask_b32_e32 v36, v54, v36, vcc
	v_rsq_f32_e32 v36, v36
	s_nop 0
	v_mul_f32_e32 v38, 0x45800000, v36
	v_cndmask_b32_e32 v36, v36, v38, vcc
	v_pk_fma_f32 v[30:31], v[30:31], v[36:37], v[158:159] op_sel_hi:[1,0,1]
	v_pk_fma_f32 v[32:33], v[32:33], v[36:37], v[160:161] op_sel_hi:[1,0,1]
	v_mul_f32_e32 v38, 0xbfb8aa3b, v30
	v_exp_f32_e32 v38, v38
	v_mul_f32_e32 v39, 0xbfb8aa3b, v31
	v_exp_f32_e32 v39, v39
	v_pk_fma_f32 v[26:27], v[26:27], v[36:37], v[150:151] op_sel_hi:[1,0,1]
	v_add_f32_e32 v38, 1.0, v38
	v_rcp_f32_e32 v38, v38
	v_pk_fma_f32 v[28:29], v[28:29], v[36:37], v[152:153] op_sel_hi:[1,0,1]
	v_pk_fma_f32 v[22:23], v[22:23], v[36:37], v[142:143] op_sel_hi:[1,0,1]
	v_pk_fma_f32 v[24:25], v[24:25], v[36:37], v[144:145] op_sel_hi:[1,0,1]
	v_mul_f32_e32 v30, v30, v38
	v_mul_f32_e32 v26, v26, v30
	v_add_f32_e32 v30, 1.0, v39
	v_mul_f32_e32 v38, 0xbfb8aa3b, v32
	v_rcp_f32_e32 v30, v30
	v_exp_f32_e32 v38, v38
	v_mul_f32_e32 v39, 0xbfb8aa3b, v33
	v_exp_f32_e32 v39, v39
	v_mul_f32_e32 v30, v31, v30
	v_add_f32_e32 v31, 1.0, v38
	v_rcp_f32_e32 v31, v31
	v_add_f32_e32 v38, 1.0, v39
	v_rcp_f32_e32 v38, v38
	v_mul_f32_e32 v27, v27, v30
	v_mul_f32_e32 v30, v32, v31
	v_mul_f32_e32 v28, v28, v30
	v_mul_f32_e32 v30, v33, v38
	v_mul_f32_e32 v29, v29, v30
	v_mul_f32_e32 v30, 0xbfb8aa3b, v22
	v_exp_f32_e32 v30, v30
	v_mul_f32_e32 v31, 0xbfb8aa3b, v23
	v_exp_f32_e32 v31, v31
	v_pk_fma_f32 v[18:19], v[18:19], v[36:37], v[122:123] op_sel_hi:[1,0,1]
	v_add_f32_e32 v30, 1.0, v30
	v_rcp_f32_e32 v30, v30
	v_pk_fma_f32 v[20:21], v[20:21], v[36:37], v[124:125] op_sel_hi:[1,0,1]
	v_cvt_pk_bf16_f32 v26, v26, v27
	v_cvt_pk_bf16_f32 v27, v28, v29
	v_mul_f32_e32 v22, v22, v30
	v_mul_f32_e32 v18, v18, v22
	v_add_f32_e32 v22, 1.0, v31
	v_mul_f32_e32 v30, 0xbfb8aa3b, v24
	v_rcp_f32_e32 v22, v22
	v_exp_f32_e32 v30, v30
	v_mul_f32_e32 v31, 0xbfb8aa3b, v25
	v_exp_f32_e32 v31, v31
	v_mul_f32_e32 v22, v23, v22
	v_add_f32_e32 v23, 1.0, v30
	v_rcp_f32_e32 v23, v23
	v_add_f32_e32 v30, 1.0, v31
	v_rcp_f32_e32 v30, v30
	v_mul_f32_e32 v19, v19, v22
	v_mul_f32_e32 v22, v24, v23
	v_mul_f32_e32 v22, v20, v22
	v_mul_f32_e32 v20, v25, v30
	v_mul_f32_e32 v23, v21, v20
	v_cvt_pk_bf16_f32 v18, v18, v19
	v_mad_i64_i32 v[28:29], s[0:1], v58, s64, v[176:177]
	v_lshl_add_u64 v[28:29], v[28:29], 0, v[178:179]
	v_pk_mul_f32 v[20:21], v[34:35], s[46:47] op_sel_hi:[1,0]
	s_nop 0
	v_fma_f32 v19, -v20, v20, v21
	v_add_f32_e32 v19, 0x3727c5ac, v19
	v_mul_f32_e32 v24, 0x4b800000, v19
	v_cmp_gt_f32_e32 vcc, s63, v19
	v_pk_fma_f32 v[14:15], v[154:155], v[20:21], v[14:15] op_sel_hi:[1,0,1] neg_lo:[1,0,0] neg_hi:[1,0,0]
	v_pk_fma_f32 v[16:17], v[156:157], v[20:21], v[16:17] op_sel_hi:[1,0,1]
	v_cndmask_b32_e32 v19, v19, v24, vcc
	v_rsq_f32_e32 v24, v19
	v_cvt_pk_bf16_f32 v19, v22, v23
	v_mov_b32_e32 v232, v26
	v_mov_b32_e32 v233, v27
	v_mov_b32_e32 v234, v18
	v_mov_b32_e32 v235, v19
	s_nop 1
	v_permlane16_swap_b32_e32 v232, v234
	v_permlane16_swap_b32_e32 v233, v235
	global_store_dwordx4 v[28:29], v[232:235], off
	v_pk_fma_f32 v[12:13], v[148:149], v[20:21], v[12:13] op_sel_hi:[1,0,1]
	v_mul_f32_e32 v18, 0x45800000, v24
	v_cndmask_b32_e32 v18, v24, v18, vcc
	v_pk_fma_f32 v[14:15], v[14:15], v[18:19], v[158:159] op_sel_hi:[1,0,1]
	v_pk_fma_f32 v[16:17], v[16:17], v[18:19], v[160:161] op_sel_hi:[1,0,1]
	v_mul_f32_e32 v19, 0xbfb8aa3b, v14
	v_exp_f32_e32 v19, v19
	v_mul_f32_e32 v22, 0xbfb8aa3b, v15
	v_exp_f32_e32 v22, v22
	v_pk_fma_f32 v[10:11], v[146:147], v[20:21], v[10:11] op_sel_hi:[1,0,1] neg_lo:[1,0,0] neg_hi:[1,0,0]
	v_pk_fma_f32 v[12:13], v[12:13], v[18:19], v[152:153] op_sel_hi:[1,0,1]
	v_add_f32_e32 v19, 1.0, v19
	v_rcp_f32_e32 v19, v19
	v_pk_fma_f32 v[6:7], v[138:139], v[20:21], v[6:7] op_sel_hi:[1,0,1] neg_lo:[1,0,0] neg_hi:[1,0,0]
	v_pk_fma_f32 v[8:9], v[118:119], v[20:21], v[8:9] op_sel_hi:[1,0,1]
	v_pk_fma_f32 v[2:3], v[126:127], v[20:21], v[2:3] op_sel_hi:[1,0,1] neg_lo:[1,0,0] neg_hi:[1,0,0]
	v_pk_fma_f32 v[10:11], v[10:11], v[18:19], v[150:151] op_sel_hi:[1,0,1]
	v_mul_f32_e32 v14, v14, v19
	v_mul_f32_e32 v10, v10, v14
	v_add_f32_e32 v14, 1.0, v22
	v_mul_f32_e32 v19, 0xbfb8aa3b, v16
	v_rcp_f32_e32 v14, v14
	v_exp_f32_e32 v19, v19
	v_mul_f32_e32 v22, 0xbfb8aa3b, v17
	v_exp_f32_e32 v22, v22
	v_mul_f32_e32 v14, v15, v14
	v_add_f32_e32 v15, 1.0, v19
	v_rcp_f32_e32 v15, v15
	v_add_f32_e32 v19, 1.0, v22
	v_rcp_f32_e32 v19, v19
	v_mul_f32_e32 v11, v11, v14
	v_mul_f32_e32 v14, v16, v15
	v_mul_f32_e32 v12, v12, v14
	v_mul_f32_e32 v14, v17, v19
	v_mul_f32_e32 v13, v13, v14
	v_cvt_pk_bf16_f32 v10, v10, v11
	v_cvt_pk_bf16_f32 v11, v12, v13
	v_mad_i64_i32 v[12:13], s[0:1], v37, s64, v[176:177]
	v_lshl_add_u64 v[12:13], v[12:13], 0, v[178:179]
	v_pk_fma_f32 v[6:7], v[6:7], v[18:19], v[142:143] op_sel_hi:[1,0,1]
	v_mov_b32_e32 v232, v10
	v_mov_b32_e32 v233, v11
	v_mul_f32_e32 v10, 0xbfb8aa3b, v6
	v_exp_f32_e32 v10, v10
	v_mul_f32_e32 v11, 0xbfb8aa3b, v7
	v_exp_f32_e32 v11, v11
	v_pk_fma_f32 v[8:9], v[8:9], v[18:19], v[144:145] op_sel_hi:[1,0,1]
	v_add_f32_e32 v10, 1.0, v10
	v_rcp_f32_e32 v10, v10
	v_pk_fma_f32 v[2:3], v[2:3], v[18:19], v[122:123] op_sel_hi:[1,0,1]
	v_pk_fma_f32 v[4:5], v[114:115], v[20:21], v[4:5] op_sel_hi:[1,0,1]
	s_and_b64 vcc, exec, s[6:7]
	v_mul_f32_e32 v6, v6, v10
	v_mul_f32_e32 v2, v2, v6
	v_add_f32_e32 v6, 1.0, v11
	v_mul_f32_e32 v10, 0xbfb8aa3b, v8
	v_rcp_f32_e32 v6, v6
	v_exp_f32_e32 v10, v10
	v_mul_f32_e32 v11, 0xbfb8aa3b, v9
	v_exp_f32_e32 v11, v11
	v_mul_f32_e32 v6, v7, v6
	v_add_f32_e32 v7, 1.0, v10
	v_rcp_f32_e32 v7, v7
	v_add_f32_e32 v10, 1.0, v11
	v_rcp_f32_e32 v10, v10
	v_pk_fma_f32 v[4:5], v[4:5], v[18:19], v[124:125] op_sel_hi:[1,0,1]
	v_mul_f32_e32 v3, v3, v6
	v_mul_f32_e32 v6, v8, v7
	v_mul_f32_e32 v4, v4, v6
	v_mul_f32_e32 v6, v9, v10
	v_mul_f32_e32 v5, v5, v6
	v_cvt_pk_bf16_f32 v2, v2, v3
	v_cvt_pk_bf16_f32 v3, v4, v5
	v_mov_b32_e32 v234, v2
	v_mov_b32_e32 v235, v3
	s_nop 1
	v_permlane16_swap_b32_e32 v232, v234
	v_permlane16_swap_b32_e32 v233, v235
	global_store_dwordx4 v[12:13], v[232:235], off
	s_cbranch_vccnz .LBB0_1105
